# grid barriers: waiting workgroups poll the top-level generation word directly instead of the per-XCD one
# baseline (speedup 1.0000x reference)
.LBB0_38:
	s_or_b64 exec, exec, s[18:19]
	v_cvt_f32_u32_e32 v5, v3
	s_waitcnt vmcnt(0)
	v_readfirstlane_b32 s6, v4
	v_sub_u32_e32 v4, 0, v3
	v_rcp_iflag_f32_e32 v5, v5
	v_add_u32_e32 v6, s6, v2
	v_mul_f32_e32 v5, 0x4f7ffffe, v5
	v_cvt_u32_f32_e32 v5, v5
	v_mul_lo_u32 v2, v4, v5
	v_mul_hi_u32 v2, v5, v2
	v_add_u32_e32 v2, v5, v2
	v_mul_hi_u32 v2, v6, v2
	v_mul_lo_u32 v4, v2, v3
	v_sub_u32_e32 v4, v6, v4
	v_add_u32_e32 v5, 1, v2
	v_cmp_ge_u32_e32 vcc, v4, v3
	s_nop 1
	v_cndmask_b32_e32 v2, v2, v5, vcc
	v_sub_u32_e32 v5, v4, v3
	v_cndmask_b32_e32 v4, v4, v5, vcc
	v_add_u32_e32 v5, 1, v2
	v_cmp_ge_u32_e32 vcc, v4, v3
	v_add_u32_e32 v4, 1, v6
	s_nop 0
	v_cndmask_b32_e32 v2, v2, v5, vcc
	v_mul_lo_u32 v5, v3, v2
	v_add_u32_e32 v3, v5, v3
	v_cmp_ne_u32_e32 vcc, v4, v3
	s_and_saveexec_b64 s[6:7], vcc
	s_xor_b64 s[16:17], exec, s[6:7]
	s_cbranch_execz .LBB0_52
	s_waitcnt lgkmcnt(0)
	s_branch .Lb0_defer
	v_mov_b32_e32 v1, 0x7500
	global_load_dword v1, v1, s[68:69] sc1
	s_add_u32 s22, s68, 0x7500
	s_addc_u32 s23, s69, 0
	s_waitcnt vmcnt(0)
	v_cmp_eq_u32_e32 vcc, v1, v2
	s_and_saveexec_b64 s[18:19], vcc
	s_cbranch_execz .LBB0_51
	s_add_u32 s20, s68, 0x4200
	s_addc_u32 s21, s69, 0
	s_mov_b32 s6, 1
	s_mov_b64 s[24:25], 0
	v_mov_b32_e32 v1, 0
	s_branch .LBB0_42
.Lb0_defer:
	s_add_u32 s22, s68, 0x7500
	s_addc_u32 s23, s69, 0
	v_mov_b32_e32 v1, 0x24200
	v_mov_b32_e32 v4, 1
	v_mov_b32_e32 v5, s22
	v_mov_b32_e32 v6, s23
	ds_write_b32 v1, v4
	ds_write_b32 v1, v2 offset:4
	ds_write_b32 v1, v5 offset:8
	ds_write_b32 v1, v6 offset:12
	s_branch .LBB0_52

.Lb1_117:
	s_or_b64 exec, exec, s[22:23]
	v_cvt_f32_u32_e32 v145, v143
	s_waitcnt vmcnt(0)
	v_readfirstlane_b32 s6, v144
	v_sub_u32_e32 v144, 0, v143
	v_rcp_iflag_f32_e32 v145, v145
	v_add_u32_e32 v146, s6, v142
	v_mul_f32_e32 v145, 0x4f7ffffe, v145
	v_cvt_u32_f32_e32 v145, v145
	v_mul_lo_u32 v142, v144, v145
	v_mul_hi_u32 v142, v145, v142
	v_add_u32_e32 v142, v145, v142
	v_mul_hi_u32 v142, v146, v142
	v_mul_lo_u32 v144, v142, v143
	v_sub_u32_e32 v144, v146, v144
	v_add_u32_e32 v145, 1, v142
	v_cmp_ge_u32_e32 vcc, v144, v143
	s_nop 1
	v_cndmask_b32_e32 v142, v142, v145, vcc
	v_sub_u32_e32 v145, v144, v143
	v_cndmask_b32_e32 v144, v144, v145, vcc
	v_add_u32_e32 v145, 1, v142
	v_cmp_ge_u32_e32 vcc, v144, v143
	v_add_u32_e32 v144, 1, v146
	s_nop 0
	v_cndmask_b32_e32 v142, v142, v145, vcc
	v_mul_lo_u32 v145, v143, v142
	v_add_u32_e32 v143, v145, v143
	v_cmp_ne_u32_e32 vcc, v144, v143
	s_and_saveexec_b64 s[6:7], vcc
	s_xor_b64 s[20:21], exec, s[6:7]
	s_cbranch_execz .Lb1_131
	s_waitcnt lgkmcnt(0)
	s_branch .Lb1_defer
	v_mov_b32_e32 v140, 0x7500
	global_load_dword v140, v140, s[68:69] sc1
	s_add_u32 s56, s68, 0x7500
	s_addc_u32 s57, s69, 0
	s_waitcnt vmcnt(0)
	v_cmp_eq_u32_e32 vcc, v140, v142
	s_and_saveexec_b64 s[22:23], vcc
	s_cbranch_execz .Lb1_130
	s_add_u32 s54, s68, 0x4200
	s_addc_u32 s55, s69, 0
	s_mov_b32 s6, 1
	s_mov_b64 s[58:59], 0
	v_mov_b32_e32 v140, 0
	s_branch .Lb1_121

.Lb1_defer:
	s_add_u32 s56, s68, 0x7500
	s_addc_u32 s57, s69, 0
	v_mov_b32_e32 v140, 0x24200
	v_mov_b32_e32 v144, 1
	v_mov_b32_e32 v145, s56
	v_mov_b32_e32 v146, s57
	ds_write_b32 v140, v144
	ds_write_b32 v140, v142 offset:4
	ds_write_b32 v140, v145 offset:8
	ds_write_b32 v140, v146 offset:12
	s_branch .Lb1_131

.LBB0_214:
	s_or_b64 exec, exec, s[10:11]
	v_cvt_f32_u32_e32 v5, v3
	s_waitcnt vmcnt(0)
	v_readfirstlane_b32 s4, v4
	v_sub_u32_e32 v4, 0, v3
	v_rcp_iflag_f32_e32 v5, v5
	v_add_u32_e32 v6, s4, v2
	v_mul_f32_e32 v5, 0x4f7ffffe, v5
	v_cvt_u32_f32_e32 v5, v5
	v_mul_lo_u32 v2, v4, v5
	v_mul_hi_u32 v2, v5, v2
	v_add_u32_e32 v2, v5, v2
	v_mul_hi_u32 v2, v6, v2
	v_mul_lo_u32 v4, v2, v3
	v_sub_u32_e32 v4, v6, v4
	v_add_u32_e32 v5, 1, v2
	v_cmp_ge_u32_e32 vcc, v4, v3
	s_nop 1
	v_cndmask_b32_e32 v2, v2, v5, vcc
	v_sub_u32_e32 v5, v4, v3
	v_cndmask_b32_e32 v4, v4, v5, vcc
	v_add_u32_e32 v5, 1, v2
	v_cmp_ge_u32_e32 vcc, v4, v3
	v_add_u32_e32 v4, 1, v6
	s_nop 0
	v_cndmask_b32_e32 v2, v2, v5, vcc
	v_mul_lo_u32 v5, v3, v2
	v_add_u32_e32 v3, v5, v3
	v_cmp_ne_u32_e32 vcc, v4, v3
	s_and_saveexec_b64 s[4:5], vcc
	s_xor_b64 s[4:5], exec, s[4:5]
	s_cbranch_execz .LBB0_228
	s_waitcnt lgkmcnt(0)
	v_mov_b32_e32 v1, 0x7500
	global_load_dword v1, v1, s[68:69] sc1
	s_add_u32 s58, s68, 0x7500
	s_addc_u32 s59, s69, 0
	s_waitcnt vmcnt(0)
	v_cmp_eq_u32_e32 vcc, v1, v2
	s_and_saveexec_b64 s[10:11], vcc
	s_cbranch_execz .LBB0_227
	s_add_u32 s56, s68, 0x4200
	s_addc_u32 s57, s69, 0
	s_mov_b32 s6, 1
	s_mov_b64 s[60:61], 0
	v_mov_b32_e32 v1, 0
	s_branch .LBB0_218

.LBB0_473:
	s_or_b64 exec, exec, s[8:9]
	v_cvt_f32_u32_e32 v5, v3
	s_waitcnt vmcnt(0)
	v_readfirstlane_b32 s4, v4
	v_sub_u32_e32 v4, 0, v3
	v_rcp_iflag_f32_e32 v5, v5
	v_add_u32_e32 v6, s4, v2
	v_mul_f32_e32 v5, 0x4f7ffffe, v5
	v_cvt_u32_f32_e32 v5, v5
	v_mul_lo_u32 v2, v4, v5
	v_mul_hi_u32 v2, v5, v2
	v_add_u32_e32 v2, v5, v2
	v_mul_hi_u32 v2, v6, v2
	v_mul_lo_u32 v4, v2, v3
	v_sub_u32_e32 v4, v6, v4
	v_add_u32_e32 v5, 1, v2
	v_cmp_ge_u32_e32 vcc, v4, v3
	s_nop 1
	v_cndmask_b32_e32 v2, v2, v5, vcc
	v_sub_u32_e32 v5, v4, v3
	v_cndmask_b32_e32 v4, v4, v5, vcc
	v_add_u32_e32 v5, 1, v2
	v_cmp_ge_u32_e32 vcc, v4, v3
	v_add_u32_e32 v4, 1, v6
	s_nop 0
	v_cndmask_b32_e32 v2, v2, v5, vcc
	v_mul_lo_u32 v5, v3, v2
	v_add_u32_e32 v3, v5, v3
	v_cmp_ne_u32_e32 vcc, v4, v3
	s_and_saveexec_b64 s[4:5], vcc
	s_xor_b64 s[4:5], exec, s[4:5]
	s_cbranch_execz .LBB0_487
	s_waitcnt lgkmcnt(0)
	s_branch .Lp3d_defer
	v_mov_b32_e32 v1, 0x7500
	global_load_dword v1, v1, s[68:69] sc1
	s_add_u32 s44, s68, 0x7500
	s_addc_u32 s45, s69, 0
	s_waitcnt vmcnt(0)
	v_cmp_eq_u32_e32 vcc, v1, v2
	s_and_saveexec_b64 s[8:9], vcc
	s_cbranch_execz .LBB0_486
	s_add_u32 s10, s68, 0x4200
	s_addc_u32 s11, s69, 0
	s_mov_b32 s6, 1
	s_mov_b64 s[46:47], 0
	v_mov_b32_e32 v1, 0
	s_branch .LBB0_477
.Lp3d_defer:
	s_add_u32 s44, s68, 0x7500
	s_addc_u32 s45, s69, 0
	v_mov_b32_e32 v1, 0x24200
	v_mov_b32_e32 v4, 1
	v_mov_b32_e32 v5, s44
	v_mov_b32_e32 v6, s45
	ds_write_b32 v1, v4
	ds_write_b32 v1, v2 offset:4
	ds_write_b32 v1, v5 offset:8
	ds_write_b32 v1, v6 offset:12
	s_branch .LBB0_487

.LBB0_888:
	s_or_b64 exec, exec, s[8:9]
	v_cvt_f32_u32_e32 v5, v3
	s_waitcnt vmcnt(0)
	v_readfirstlane_b32 s4, v4
	v_sub_u32_e32 v4, 0, v3
	v_rcp_iflag_f32_e32 v5, v5
	v_add_u32_e32 v6, s4, v2
	v_mul_f32_e32 v5, 0x4f7ffffe, v5
	v_cvt_u32_f32_e32 v5, v5
	v_mul_lo_u32 v2, v4, v5
	v_mul_hi_u32 v2, v5, v2
	v_add_u32_e32 v2, v5, v2
	v_mul_hi_u32 v2, v6, v2
	v_mul_lo_u32 v4, v2, v3
	v_sub_u32_e32 v4, v6, v4
	v_add_u32_e32 v5, 1, v2
	v_cmp_ge_u32_e32 vcc, v4, v3
	s_nop 1
	v_cndmask_b32_e32 v2, v2, v5, vcc
	v_sub_u32_e32 v5, v4, v3
	v_cndmask_b32_e32 v4, v4, v5, vcc
	v_add_u32_e32 v5, 1, v2
	v_cmp_ge_u32_e32 vcc, v4, v3
	v_add_u32_e32 v4, 1, v6
	s_nop 0
	v_cndmask_b32_e32 v2, v2, v5, vcc
	v_mul_lo_u32 v5, v3, v2
	v_add_u32_e32 v3, v5, v3
	v_cmp_ne_u32_e32 vcc, v4, v3
	s_and_saveexec_b64 s[4:5], vcc
	s_xor_b64 s[4:5], exec, s[4:5]
	s_cbranch_execz .LBB0_902
	s_waitcnt lgkmcnt(0)
	v_mov_b32_e32 v1, 0x7500
	global_load_dword v1, v1, s[68:69] sc1
	s_add_u32 s24, s68, 0x7500
	s_addc_u32 s25, s69, 0
	s_waitcnt vmcnt(0)
	v_cmp_eq_u32_e32 vcc, v1, v2
	s_and_saveexec_b64 s[8:9], vcc
	s_cbranch_execz .LBB0_901
	s_add_u32 s10, s68, 0x4200
	s_addc_u32 s11, s69, 0
	s_mov_b32 s6, 1
	s_mov_b64 s[40:41], 0
	v_mov_b32_e32 v1, 0
	s_branch .LBB0_892

.LBB0_1004:
	s_or_b64 exec, exec, s[8:9]
	v_cvt_f32_u32_e32 v5, v3
	s_waitcnt vmcnt(0)
	v_readfirstlane_b32 s4, v4
	v_sub_u32_e32 v4, 0, v3
	v_rcp_iflag_f32_e32 v5, v5
	v_add_u32_e32 v6, s4, v2
	v_mul_f32_e32 v5, 0x4f7ffffe, v5
	v_cvt_u32_f32_e32 v5, v5
	v_mul_lo_u32 v2, v4, v5
	v_mul_hi_u32 v2, v5, v2
	v_add_u32_e32 v2, v5, v2
	v_mul_hi_u32 v2, v6, v2
	v_mul_lo_u32 v4, v2, v3
	v_sub_u32_e32 v4, v6, v4
	v_add_u32_e32 v5, 1, v2
	v_cmp_ge_u32_e32 vcc, v4, v3
	s_nop 1
	v_cndmask_b32_e32 v2, v2, v5, vcc
	v_sub_u32_e32 v5, v4, v3
	v_cndmask_b32_e32 v4, v4, v5, vcc
	v_add_u32_e32 v5, 1, v2
	v_cmp_ge_u32_e32 vcc, v4, v3
	v_add_u32_e32 v4, 1, v6
	s_nop 0
	v_cndmask_b32_e32 v2, v2, v5, vcc
	v_mul_lo_u32 v5, v3, v2
	v_add_u32_e32 v3, v5, v3
	v_cmp_ne_u32_e32 vcc, v4, v3
	s_and_saveexec_b64 s[4:5], vcc
	s_xor_b64 s[4:5], exec, s[4:5]
	s_cbranch_execz .LBB0_1018
	s_waitcnt lgkmcnt(0)
	v_mov_b32_e32 v1, 0x7500
	global_load_dword v1, v1, s[68:69] sc1
	s_add_u32 s36, s68, 0x7500
	s_addc_u32 s37, s69, 0
	s_waitcnt vmcnt(0)
	v_cmp_eq_u32_e32 vcc, v1, v2
	s_and_saveexec_b64 s[8:9], vcc
	s_cbranch_execz .LBB0_1017
	s_add_u32 s10, s68, 0x4200
	s_addc_u32 s11, s69, 0
	s_mov_b32 s6, 1
	s_mov_b64 s[38:39], 0
	v_mov_b32_e32 v1, 0
	s_branch .LBB0_1008

.LBB0_1096:
	s_or_b64 exec, exec, s[10:11]
	v_cvt_f32_u32_e32 v5, v3
	s_waitcnt vmcnt(0)
	v_readfirstlane_b32 s6, v4
	v_sub_u32_e32 v4, 0, v3
	v_rcp_iflag_f32_e32 v5, v5
	v_add_u32_e32 v6, s6, v2
	v_mul_f32_e32 v5, 0x4f7ffffe, v5
	v_cvt_u32_f32_e32 v5, v5
	v_mul_lo_u32 v2, v4, v5
	v_mul_hi_u32 v2, v5, v2
	v_add_u32_e32 v2, v5, v2
	v_mul_hi_u32 v2, v6, v2
	v_mul_lo_u32 v4, v2, v3
	v_sub_u32_e32 v4, v6, v4
	v_add_u32_e32 v5, 1, v2
	v_cmp_ge_u32_e32 vcc, v4, v3
	s_nop 1
	v_cndmask_b32_e32 v2, v2, v5, vcc
	v_sub_u32_e32 v5, v4, v3
	v_cndmask_b32_e32 v4, v4, v5, vcc
	v_add_u32_e32 v5, 1, v2
	v_cmp_ge_u32_e32 vcc, v4, v3
	v_add_u32_e32 v4, 1, v6
	s_nop 0
	v_cndmask_b32_e32 v2, v2, v5, vcc
	v_mul_lo_u32 v5, v3, v2
	v_add_u32_e32 v3, v5, v3
	v_cmp_ne_u32_e32 vcc, v4, v3
	s_and_saveexec_b64 s[6:7], vcc
	s_xor_b64 s[8:9], exec, s[6:7]
	s_cbranch_execz .LBB0_1110
	s_waitcnt lgkmcnt(0)
	v_mov_b32_e32 v1, 0x7500
	global_load_dword v1, v1, s[68:69] sc1
	s_add_u32 s18, s68, 0x7500
	s_addc_u32 s19, s69, 0
	s_waitcnt vmcnt(0)
	v_cmp_eq_u32_e32 vcc, v1, v2
	s_and_saveexec_b64 s[10:11], vcc
	s_cbranch_execz .LBB0_1109
	s_add_u32 s16, s68, 0x4200
	s_addc_u32 s17, s69, 0
	s_mov_b32 s6, 1
	s_mov_b64 s[22:23], 0
	v_mov_b32_e32 v1, 0
	s_branch .LBB0_1100

.LBB0_1216:
	s_or_b64 exec, exec, s[6:7]
	v_cvt_f32_u32_e32 v4, v2
	s_waitcnt vmcnt(0)
	v_readfirstlane_b32 s4, v3
	v_sub_u32_e32 v3, 0, v2
	v_rcp_iflag_f32_e32 v4, v4
	v_add_u32_e32 v5, s4, v1
	v_mul_f32_e32 v4, 0x4f7ffffe, v4
	v_cvt_u32_f32_e32 v4, v4
	v_mul_lo_u32 v1, v3, v4
	v_mul_hi_u32 v1, v4, v1
	v_add_u32_e32 v1, v4, v1
	v_mul_hi_u32 v1, v5, v1
	v_mul_lo_u32 v3, v1, v2
	v_sub_u32_e32 v3, v5, v3
	v_add_u32_e32 v4, 1, v1
	v_cmp_ge_u32_e32 vcc, v3, v2
	s_nop 1
	v_cndmask_b32_e32 v1, v1, v4, vcc
	v_sub_u32_e32 v4, v3, v2
	v_cndmask_b32_e32 v3, v3, v4, vcc
	v_add_u32_e32 v4, 1, v1
	v_cmp_ge_u32_e32 vcc, v3, v2
	v_add_u32_e32 v3, 1, v5
	s_nop 0
	v_cndmask_b32_e32 v1, v1, v4, vcc
	v_mul_lo_u32 v4, v2, v1
	v_add_u32_e32 v2, v4, v2
	v_cmp_ne_u32_e32 vcc, v3, v2
	s_and_saveexec_b64 s[4:5], vcc
	s_xor_b64 s[4:5], exec, s[4:5]
	s_cbranch_execz .LBB0_1230
	s_waitcnt lgkmcnt(0)
	v_mov_b32_e32 v0, 0x7500
	global_load_dword v0, v0, s[68:69] sc1
	s_add_u32 s10, s68, 0x7500
	s_addc_u32 s11, s69, 0
	s_waitcnt vmcnt(0)
	v_cmp_eq_u32_e32 vcc, v0, v1
	s_and_saveexec_b64 s[6:7], vcc
	s_cbranch_execz .LBB0_1229
	s_add_u32 s8, s68, 0x4200
	s_addc_u32 s9, s69, 0
	s_mov_b32 s15, 1
	s_mov_b64 s[12:13], 0
	v_mov_b32_e32 v0, 0
	s_branch .LBB0_1220
